# barrier: all pollers watch the cross-XCC arrival counter itself (target (round+1)*nx), dropping the generation-word hop from the release chain
# baseline (speedup 1.0000x reference)
.LBB0_41:
	s_or_b64 exec, exec, s[8:9]
	v_cvt_f32_u32_e32 v4, v2
	s_waitcnt vmcnt(0)
	v_readfirstlane_b32 s6, v3
	v_sub_u32_e32 v3, 0, v2
	v_rcp_iflag_f32_e32 v4, v4
	v_add_u32_e32 v5, s6, v1
	v_mul_f32_e32 v4, 0x4f7ffffe, v4
	v_cvt_u32_f32_e32 v4, v4
	v_mul_lo_u32 v1, v3, v4
	v_mul_hi_u32 v1, v4, v1
	v_add_u32_e32 v1, v4, v1
	v_mul_hi_u32 v1, v5, v1
	v_mul_lo_u32 v3, v1, v2
	v_sub_u32_e32 v3, v5, v3
	v_add_u32_e32 v4, 1, v1
	v_cmp_ge_u32_e32 vcc, v3, v2
	s_nop 1
	v_cndmask_b32_e32 v1, v1, v4, vcc
	v_sub_u32_e32 v4, v3, v2
	v_cndmask_b32_e32 v3, v3, v4, vcc
	v_add_u32_e32 v4, 1, v1
	v_cmp_ge_u32_e32 vcc, v3, v2
	v_add_u32_e32 v3, 1, v5
	s_nop 0
	v_cndmask_b32_e32 v1, v1, v4, vcc
	v_mul_lo_u32 v4, v2, v1
	v_add_u32_e32 v2, v4, v2
	v_cmp_ne_u32_e32 vcc, v3, v2
	s_and_saveexec_b64 s[6:7], vcc
	s_xor_b64 s[6:7], exec, s[6:7]
	s_cbranch_execz .LBB0_55
	s_waitcnt lgkmcnt(0)
	v_add_u32_e32 v1, 1, v1
	v_mul_lo_u32 v1, v1, v0
	v_mov_b32_e32 v0, 0
	s_add_u32 s14, s74, 0x1e353400
	s_addc_u32 s15, s75, 0
	global_load_dword v0, v0, s[14:15] sc1
	s_waitcnt vmcnt(0)
	v_cmp_lt_u32_e32 vcc, v0, v1
	s_and_saveexec_b64 s[8:9], vcc
	s_cbranch_execz .LBB0_54
	s_add_u32 s10, s74, 0x1e350200
	s_addc_u32 s11, s75, 0
	s_mov_b32 s13, 1
	s_mov_b64 s[34:35], 0
	v_mov_b32_e32 v0, 0
	s_branch .LBB0_45

.LBB0_49:
	global_load_dword v2, v0, s[14:15] sc1
	s_add_i32 s13, s13, 1
	s_mov_b64 s[40:41], -1
	s_waitcnt vmcnt(0)
	v_cmp_ge_u32_e32 vcc, v2, v1
	s_orn2_b64 s[38:39], vcc, exec
	s_branch .LBB0_44

.LBB0_58:
	s_or_b64 exec, exec, s[8:9]
	v_cvt_f32_u32_e32 v3, v0
	s_waitcnt vmcnt(0)
	v_readfirstlane_b32 s6, v2
	s_add_u32 s8, s74, 0x1e353500
	s_addc_u32 s9, s75, 0
	v_rcp_iflag_f32_e32 v3, v3
	v_add_u32_e32 v1, s6, v1
	v_add_u32_e32 v4, 1, v1
	s_mov_b64 s[10:11], -1
	v_mul_f32_e32 v2, 0x4f7ffffe, v3
	v_cvt_u32_f32_e32 v2, v2
	v_sub_u32_e32 v3, 0, v0
	v_mul_lo_u32 v3, v3, v2
	v_mul_hi_u32 v3, v2, v3
	v_add_u32_e32 v2, v2, v3
	v_mul_hi_u32 v2, v1, v2
	v_mul_lo_u32 v3, v2, v0
	v_sub_u32_e32 v1, v1, v3
	v_add_u32_e32 v5, 1, v2
	v_cmp_ge_u32_e32 vcc, v1, v0
	v_sub_u32_e32 v3, v1, v0
	s_nop 0
	v_cndmask_b32_e32 v2, v2, v5, vcc
	v_cndmask_b32_e32 v1, v1, v3, vcc
	v_add_u32_e32 v3, 1, v2
	v_cmp_ge_u32_e32 vcc, v1, v0
	s_nop 1
	v_cndmask_b32_e32 v2, v2, v3, vcc
	v_mul_lo_u32 v1, v0, v2
	v_add_u32_e32 v0, v1, v0
	v_cmp_ne_u32_e32 vcc, v4, v0
	v_mov_b32_e32 v2, v0
	v_mov_b64_e32 v[0:1], s[8:9]
	s_and_saveexec_b64 s[6:7], vcc
	s_cbranch_execz .LBB0_70
	v_mov_b32_e32 v0, 0
	global_load_dword v1, v0, s[8:9] offset:-256 sc1
	s_mov_b64 s[34:35], 0
	s_waitcnt vmcnt(0)
	v_cmp_lt_u32_e32 vcc, v1, v2
	s_and_saveexec_b64 s[14:15], vcc
	s_cbranch_execz .LBB0_69
	s_add_u32 s10, s74, 0x1e350200
	s_addc_u32 s11, s75, 0
	s_mov_b32 s13, 1
	s_branch .LBB0_62

.LBB0_66:
	global_load_dword v1, v0, s[8:9] offset:-256 sc1
	s_add_i32 s13, s13, 1
	s_mov_b64 s[38:39], -1
	s_waitcnt vmcnt(0)
	v_cmp_ge_u32_e32 vcc, v1, v2
	s_orn2_b64 s[42:43], vcc, exec
	s_branch .LBB0_61

.LBB0_164:
	s_or_b64 exec, exec, s[8:9]
	v_cvt_f32_u32_e32 v4, v2
	s_waitcnt vmcnt(0)
	v_readfirstlane_b32 s4, v3
	v_sub_u32_e32 v3, 0, v2
	v_rcp_iflag_f32_e32 v4, v4
	v_add_u32_e32 v5, s4, v1
	v_mul_f32_e32 v4, 0x4f7ffffe, v4
	v_cvt_u32_f32_e32 v4, v4
	v_mul_lo_u32 v1, v3, v4
	v_mul_hi_u32 v1, v4, v1
	v_add_u32_e32 v1, v4, v1
	v_mul_hi_u32 v1, v5, v1
	v_mul_lo_u32 v3, v1, v2
	v_sub_u32_e32 v3, v5, v3
	v_add_u32_e32 v4, 1, v1
	v_cmp_ge_u32_e32 vcc, v3, v2
	s_nop 1
	v_cndmask_b32_e32 v1, v1, v4, vcc
	v_sub_u32_e32 v4, v3, v2
	v_cndmask_b32_e32 v3, v3, v4, vcc
	v_add_u32_e32 v4, 1, v1
	v_cmp_ge_u32_e32 vcc, v3, v2
	v_add_u32_e32 v3, 1, v5
	s_nop 0
	v_cndmask_b32_e32 v1, v1, v4, vcc
	v_mul_lo_u32 v4, v2, v1
	v_add_u32_e32 v2, v4, v2
	v_cmp_ne_u32_e32 vcc, v3, v2
	s_and_saveexec_b64 s[4:5], vcc
	s_xor_b64 s[4:5], exec, s[4:5]
	s_cbranch_execz .LBB0_178
	s_waitcnt lgkmcnt(0)
	v_add_u32_e32 v1, 1, v1
	v_mul_lo_u32 v1, v1, v0
	v_mov_b32_e32 v0, 0
	s_add_u32 s14, s74, 0x1e353400
	s_addc_u32 s15, s75, 0
	global_load_dword v0, v0, s[14:15] sc1
	s_waitcnt vmcnt(0)
	v_cmp_lt_u32_e32 vcc, v0, v1
	s_and_saveexec_b64 s[8:9], vcc
	s_cbranch_execz .LBB0_177
	s_add_u32 s10, s74, 0x1e350200
	s_addc_u32 s11, s75, 0
	s_mov_b32 s13, 1
	s_mov_b64 s[34:35], 0
	v_mov_b32_e32 v0, 0
	s_branch .LBB0_168

.LBB0_181:
	s_or_b64 exec, exec, s[8:9]
	v_cvt_f32_u32_e32 v3, v0
	s_waitcnt vmcnt(0)
	v_readfirstlane_b32 s4, v2
	s_add_u32 s8, s74, 0x1e353500
	s_addc_u32 s9, s75, 0
	v_rcp_iflag_f32_e32 v3, v3
	v_add_u32_e32 v1, s4, v1
	v_add_u32_e32 v4, 1, v1
	s_mov_b64 s[10:11], -1
	v_mul_f32_e32 v2, 0x4f7ffffe, v3
	v_cvt_u32_f32_e32 v2, v2
	v_sub_u32_e32 v3, 0, v0
	v_mul_lo_u32 v3, v3, v2
	v_mul_hi_u32 v3, v2, v3
	v_add_u32_e32 v2, v2, v3
	v_mul_hi_u32 v2, v1, v2
	v_mul_lo_u32 v3, v2, v0
	v_sub_u32_e32 v1, v1, v3
	v_add_u32_e32 v5, 1, v2
	v_cmp_ge_u32_e32 vcc, v1, v0
	v_sub_u32_e32 v3, v1, v0
	s_nop 0
	v_cndmask_b32_e32 v2, v2, v5, vcc
	v_cndmask_b32_e32 v1, v1, v3, vcc
	v_add_u32_e32 v3, 1, v2
	v_cmp_ge_u32_e32 vcc, v1, v0
	s_nop 1
	v_cndmask_b32_e32 v2, v2, v3, vcc
	v_mul_lo_u32 v1, v0, v2
	v_add_u32_e32 v0, v1, v0
	v_cmp_ne_u32_e32 vcc, v4, v0
	v_mov_b32_e32 v2, v0
	v_mov_b64_e32 v[0:1], s[8:9]
	s_and_saveexec_b64 s[4:5], vcc
	s_cbranch_execz .LBB0_193
	v_mov_b32_e32 v0, 0
	global_load_dword v1, v0, s[8:9] offset:-256 sc1
	s_mov_b64 s[34:35], 0
	s_waitcnt vmcnt(0)
	v_cmp_lt_u32_e32 vcc, v1, v2
	s_and_saveexec_b64 s[14:15], vcc
	s_cbranch_execz .LBB0_192
	s_add_u32 s10, s74, 0x1e350200
	s_addc_u32 s11, s75, 0
	s_mov_b32 s13, 1
	s_branch .LBB0_185

.LBB0_306:
	s_or_b64 exec, exec, s[6:7]
	v_cvt_f32_u32_e32 v4, v2
	s_waitcnt vmcnt(0)
	v_readfirstlane_b32 s4, v3
	v_sub_u32_e32 v3, 0, v2
	v_rcp_iflag_f32_e32 v4, v4
	v_add_u32_e32 v5, s4, v1
	v_mul_f32_e32 v4, 0x4f7ffffe, v4
	v_cvt_u32_f32_e32 v4, v4
	v_mul_lo_u32 v1, v3, v4
	v_mul_hi_u32 v1, v4, v1
	v_add_u32_e32 v1, v4, v1
	v_mul_hi_u32 v1, v5, v1
	v_mul_lo_u32 v3, v1, v2
	v_sub_u32_e32 v3, v5, v3
	v_add_u32_e32 v4, 1, v1
	v_cmp_ge_u32_e32 vcc, v3, v2
	s_nop 1
	v_cndmask_b32_e32 v1, v1, v4, vcc
	v_sub_u32_e32 v4, v3, v2
	v_cndmask_b32_e32 v3, v3, v4, vcc
	v_add_u32_e32 v4, 1, v1
	v_cmp_ge_u32_e32 vcc, v3, v2
	v_add_u32_e32 v3, 1, v5
	s_nop 0
	v_cndmask_b32_e32 v1, v1, v4, vcc
	v_mul_lo_u32 v4, v2, v1
	v_add_u32_e32 v2, v4, v2
	v_cmp_ne_u32_e32 vcc, v3, v2
	s_and_saveexec_b64 s[4:5], vcc
	s_xor_b64 s[4:5], exec, s[4:5]
	s_cbranch_execz .LBB0_320
	s_waitcnt lgkmcnt(0)
	v_add_u32_e32 v1, 1, v1
	v_mul_lo_u32 v1, v1, v0
	v_mov_b32_e32 v0, 0
	s_add_u32 s14, s74, 0x1e353400
	s_addc_u32 s15, s75, 0
	global_load_dword v0, v0, s[14:15] sc1
	s_waitcnt vmcnt(0)
	v_cmp_lt_u32_e32 vcc, v0, v1
	s_and_saveexec_b64 s[6:7], vcc
	s_cbranch_execz .LBB0_319
	s_add_u32 s8, s74, 0x1e350200
	s_addc_u32 s9, s75, 0
	s_mov_b32 s13, 1
	s_mov_b64 s[34:35], 0
	v_mov_b32_e32 v0, 0
	s_branch .LBB0_310

.LBB0_323:
	s_or_b64 exec, exec, s[6:7]
	v_cvt_f32_u32_e32 v3, v0
	s_waitcnt vmcnt(0)
	v_readfirstlane_b32 s4, v2
	s_add_u32 s6, s74, 0x1e353500
	s_addc_u32 s7, s75, 0
	v_rcp_iflag_f32_e32 v3, v3
	v_add_u32_e32 v1, s4, v1
	v_add_u32_e32 v4, 1, v1
	s_mov_b64 s[8:9], -1
	v_mul_f32_e32 v2, 0x4f7ffffe, v3
	v_cvt_u32_f32_e32 v2, v2
	v_sub_u32_e32 v3, 0, v0
	v_mul_lo_u32 v3, v3, v2
	v_mul_hi_u32 v3, v2, v3
	v_add_u32_e32 v2, v2, v3
	v_mul_hi_u32 v2, v1, v2
	v_mul_lo_u32 v3, v2, v0
	v_sub_u32_e32 v1, v1, v3
	v_add_u32_e32 v5, 1, v2
	v_cmp_ge_u32_e32 vcc, v1, v0
	v_sub_u32_e32 v3, v1, v0
	s_nop 0
	v_cndmask_b32_e32 v2, v2, v5, vcc
	v_cndmask_b32_e32 v1, v1, v3, vcc
	v_add_u32_e32 v3, 1, v2
	v_cmp_ge_u32_e32 vcc, v1, v0
	s_nop 1
	v_cndmask_b32_e32 v2, v2, v3, vcc
	v_mul_lo_u32 v1, v0, v2
	v_add_u32_e32 v0, v1, v0
	v_cmp_ne_u32_e32 vcc, v4, v0
	v_mov_b32_e32 v2, v0
	v_mov_b64_e32 v[0:1], s[6:7]
	s_and_saveexec_b64 s[4:5], vcc
	s_cbranch_execz .LBB0_335
	v_mov_b32_e32 v0, 0
	global_load_dword v1, v0, s[6:7] offset:-256 sc1
	s_mov_b64 s[34:35], 0
	s_waitcnt vmcnt(0)
	v_cmp_lt_u32_e32 vcc, v1, v2
	s_and_saveexec_b64 s[14:15], vcc
	s_cbranch_execz .LBB0_334
	s_add_u32 s8, s74, 0x1e350200
	s_addc_u32 s9, s75, 0
	s_mov_b32 s13, 1
	s_branch .LBB0_327

.LBB0_331:
	global_load_dword v1, v0, s[6:7] offset:-256 sc1
	s_add_i32 s13, s13, 1
	s_mov_b64 s[38:39], -1
	s_waitcnt vmcnt(0)
	v_cmp_ge_u32_e32 vcc, v1, v2
	s_orn2_b64 s[42:43], vcc, exec
	s_branch .LBB0_326

.LBB0_460:
	s_or_b64 exec, exec, s[6:7]
	v_cvt_f32_u32_e32 v4, v2
	s_waitcnt vmcnt(0)
	v_readfirstlane_b32 s4, v3
	v_sub_u32_e32 v3, 0, v2
	v_rcp_iflag_f32_e32 v4, v4
	v_add_u32_e32 v5, s4, v1
	v_mul_f32_e32 v4, 0x4f7ffffe, v4
	v_cvt_u32_f32_e32 v4, v4
	v_mul_lo_u32 v1, v3, v4
	v_mul_hi_u32 v1, v4, v1
	v_add_u32_e32 v1, v4, v1
	v_mul_hi_u32 v1, v5, v1
	v_mul_lo_u32 v3, v1, v2
	v_sub_u32_e32 v3, v5, v3
	v_add_u32_e32 v4, 1, v1
	v_cmp_ge_u32_e32 vcc, v3, v2
	s_nop 1
	v_cndmask_b32_e32 v1, v1, v4, vcc
	v_sub_u32_e32 v4, v3, v2
	v_cndmask_b32_e32 v3, v3, v4, vcc
	v_add_u32_e32 v4, 1, v1
	v_cmp_ge_u32_e32 vcc, v3, v2
	v_add_u32_e32 v3, 1, v5
	s_nop 0
	v_cndmask_b32_e32 v1, v1, v4, vcc
	v_mul_lo_u32 v4, v2, v1
	v_add_u32_e32 v2, v4, v2
	v_cmp_ne_u32_e32 vcc, v3, v2
	s_and_saveexec_b64 s[4:5], vcc
	s_xor_b64 s[4:5], exec, s[4:5]
	s_cbranch_execz .LBB0_474
	s_waitcnt lgkmcnt(0)
	v_add_u32_e32 v1, 1, v1
	v_mul_lo_u32 v1, v1, v0
	v_mov_b32_e32 v0, 0
	s_add_u32 s10, s74, 0x1e353400
	s_addc_u32 s11, s75, 0
	global_load_dword v0, v0, s[10:11] sc1
	s_waitcnt vmcnt(0)
	v_cmp_lt_u32_e32 vcc, v0, v1
	s_and_saveexec_b64 s[6:7], vcc
	s_cbranch_execz .LBB0_473
	s_add_u32 s8, s74, 0x1e350200
	s_addc_u32 s9, s75, 0
	s_mov_b32 s13, 1
	s_mov_b64 s[14:15], 0
	v_mov_b32_e32 v0, 0
	s_branch .LBB0_464

.LBB0_468:
	global_load_dword v2, v0, s[10:11] sc1
	s_add_i32 s13, s13, 1
	s_mov_b64 s[38:39], -1
	s_waitcnt vmcnt(0)
	v_cmp_ge_u32_e32 vcc, v2, v1
	s_orn2_b64 s[36:37], vcc, exec
	s_branch .LBB0_463

.LBB0_477:
	s_or_b64 exec, exec, s[6:7]
	v_cvt_f32_u32_e32 v3, v0
	s_waitcnt vmcnt(0)
	v_readfirstlane_b32 s4, v2
	s_add_u32 s6, s74, 0x1e353500
	s_addc_u32 s7, s75, 0
	v_rcp_iflag_f32_e32 v3, v3
	v_add_u32_e32 v1, s4, v1
	v_add_u32_e32 v4, 1, v1
	s_mov_b64 s[8:9], -1
	v_mul_f32_e32 v2, 0x4f7ffffe, v3
	v_cvt_u32_f32_e32 v2, v2
	v_sub_u32_e32 v3, 0, v0
	v_mul_lo_u32 v3, v3, v2
	v_mul_hi_u32 v3, v2, v3
	v_add_u32_e32 v2, v2, v3
	v_mul_hi_u32 v2, v1, v2
	v_mul_lo_u32 v3, v2, v0
	v_sub_u32_e32 v1, v1, v3
	v_add_u32_e32 v5, 1, v2
	v_cmp_ge_u32_e32 vcc, v1, v0
	v_sub_u32_e32 v3, v1, v0
	s_nop 0
	v_cndmask_b32_e32 v2, v2, v5, vcc
	v_cndmask_b32_e32 v1, v1, v3, vcc
	v_add_u32_e32 v3, 1, v2
	v_cmp_ge_u32_e32 vcc, v1, v0
	s_nop 1
	v_cndmask_b32_e32 v2, v2, v3, vcc
	v_mul_lo_u32 v1, v0, v2
	v_add_u32_e32 v0, v1, v0
	v_cmp_ne_u32_e32 vcc, v4, v0
	v_mov_b32_e32 v2, v0
	v_mov_b64_e32 v[0:1], s[6:7]
	s_and_saveexec_b64 s[4:5], vcc
	s_cbranch_execz .LBB0_489
	v_mov_b32_e32 v0, 0
	global_load_dword v1, v0, s[6:7] offset:-256 sc1
	s_mov_b64 s[14:15], 0
	s_waitcnt vmcnt(0)
	v_cmp_lt_u32_e32 vcc, v1, v2
	s_and_saveexec_b64 s[10:11], vcc
	s_cbranch_execz .LBB0_488
	s_add_u32 s8, s74, 0x1e350200
	s_addc_u32 s9, s75, 0
	s_mov_b32 s13, 1
	s_branch .LBB0_481

.LBB0_485:
	global_load_dword v1, v0, s[6:7] offset:-256 sc1
	s_add_i32 s13, s13, 1
	s_mov_b64 s[36:37], -1
	s_waitcnt vmcnt(0)
	v_cmp_ge_u32_e32 vcc, v1, v2
	s_orn2_b64 s[40:41], vcc, exec
	s_branch .LBB0_480

.LBB0_855:
	s_or_b64 exec, exec, s[8:9]
	v_cvt_f32_u32_e32 v4, v2
	s_waitcnt vmcnt(0)
	v_readfirstlane_b32 s6, v3
	v_sub_u32_e32 v3, 0, v2
	v_rcp_iflag_f32_e32 v4, v4
	v_add_u32_e32 v5, s6, v1
	v_mul_f32_e32 v4, 0x4f7ffffe, v4
	v_cvt_u32_f32_e32 v4, v4
	v_mul_lo_u32 v1, v3, v4
	v_mul_hi_u32 v1, v4, v1
	v_add_u32_e32 v1, v4, v1
	v_mul_hi_u32 v1, v5, v1
	v_mul_lo_u32 v3, v1, v2
	v_sub_u32_e32 v3, v5, v3
	v_add_u32_e32 v4, 1, v1
	v_cmp_ge_u32_e32 vcc, v3, v2
	s_nop 1
	v_cndmask_b32_e32 v1, v1, v4, vcc
	v_sub_u32_e32 v4, v3, v2
	v_cndmask_b32_e32 v3, v3, v4, vcc
	v_add_u32_e32 v4, 1, v1
	v_cmp_ge_u32_e32 vcc, v3, v2
	v_add_u32_e32 v3, 1, v5
	s_nop 0
	v_cndmask_b32_e32 v1, v1, v4, vcc
	v_mul_lo_u32 v4, v2, v1
	v_add_u32_e32 v2, v4, v2
	v_cmp_ne_u32_e32 vcc, v3, v2
	s_and_saveexec_b64 s[6:7], vcc
	s_xor_b64 s[6:7], exec, s[6:7]
	s_cbranch_execz .LBB0_869
	s_waitcnt lgkmcnt(0)
	v_add_u32_e32 v1, 1, v1
	v_mul_lo_u32 v1, v1, v0
	v_mov_b32_e32 v0, 0
	s_add_u32 s34, s74, 0x1e353400
	s_addc_u32 s35, s75, 0
	global_load_dword v0, v0, s[34:35] sc1
	s_waitcnt vmcnt(0)
	v_cmp_lt_u32_e32 vcc, v0, v1
	s_and_saveexec_b64 s[8:9], vcc
	s_cbranch_execz .LBB0_868
	s_add_u32 s14, s74, 0x1e350200
	s_addc_u32 s15, s75, 0
	s_mov_b32 s13, 1
	s_mov_b64 s[36:37], 0
	v_mov_b32_e32 v0, 0
	s_branch .LBB0_859

.LBB0_863:
	global_load_dword v2, v0, s[34:35] sc1
	s_add_i32 s13, s13, 1
	s_mov_b64 s[42:43], -1
	s_waitcnt vmcnt(0)
	v_cmp_ge_u32_e32 vcc, v2, v1
	s_orn2_b64 s[40:41], vcc, exec
	s_branch .LBB0_858

.LBB0_872:
	s_or_b64 exec, exec, s[8:9]
	v_cvt_f32_u32_e32 v3, v0
	s_waitcnt vmcnt(0)
	v_readfirstlane_b32 s6, v2
	s_add_u32 s8, s74, 0x1e353500
	s_addc_u32 s9, s75, 0
	v_rcp_iflag_f32_e32 v3, v3
	v_add_u32_e32 v1, s6, v1
	v_add_u32_e32 v4, 1, v1
	s_mov_b64 s[14:15], -1
	v_mul_f32_e32 v2, 0x4f7ffffe, v3
	v_cvt_u32_f32_e32 v2, v2
	v_sub_u32_e32 v3, 0, v0
	v_mul_lo_u32 v3, v3, v2
	v_mul_hi_u32 v3, v2, v3
	v_add_u32_e32 v2, v2, v3
	v_mul_hi_u32 v2, v1, v2
	v_mul_lo_u32 v3, v2, v0
	v_sub_u32_e32 v1, v1, v3
	v_add_u32_e32 v5, 1, v2
	v_cmp_ge_u32_e32 vcc, v1, v0
	v_sub_u32_e32 v3, v1, v0
	s_nop 0
	v_cndmask_b32_e32 v2, v2, v5, vcc
	v_cndmask_b32_e32 v1, v1, v3, vcc
	v_add_u32_e32 v3, 1, v2
	v_cmp_ge_u32_e32 vcc, v1, v0
	s_nop 1
	v_cndmask_b32_e32 v2, v2, v3, vcc
	v_mul_lo_u32 v1, v0, v2
	v_add_u32_e32 v0, v1, v0
	v_cmp_ne_u32_e32 vcc, v4, v0
	v_mov_b32_e32 v2, v0
	v_mov_b64_e32 v[0:1], s[8:9]
	s_and_saveexec_b64 s[6:7], vcc
	s_cbranch_execz .LBB0_884
	v_mov_b32_e32 v0, 0
	global_load_dword v1, v0, s[8:9] offset:-256 sc1
	s_mov_b64 s[36:37], 0
	s_waitcnt vmcnt(0)
	v_cmp_lt_u32_e32 vcc, v1, v2
	s_and_saveexec_b64 s[34:35], vcc
	s_cbranch_execz .LBB0_883
	s_add_u32 s14, s74, 0x1e350200
	s_addc_u32 s15, s75, 0
	s_mov_b32 s13, 1
	s_branch .LBB0_876

.LBB0_880:
	global_load_dword v1, v0, s[8:9] offset:-256 sc1
	s_add_i32 s13, s13, 1
	s_mov_b64 s[40:41], -1
	s_waitcnt vmcnt(0)
	v_cmp_ge_u32_e32 vcc, v1, v2
	s_orn2_b64 s[44:45], vcc, exec
	s_branch .LBB0_875

.LBB0_1353:
	s_or_b64 exec, exec, s[8:9]
	v_cvt_f32_u32_e32 v4, v2
	s_waitcnt vmcnt(0)
	v_readfirstlane_b32 s4, v3
	v_sub_u32_e32 v3, 0, v2
	v_rcp_iflag_f32_e32 v4, v4
	v_add_u32_e32 v5, s4, v1
	v_mul_f32_e32 v4, 0x4f7ffffe, v4
	v_cvt_u32_f32_e32 v4, v4
	v_mul_lo_u32 v1, v3, v4
	v_mul_hi_u32 v1, v4, v1
	v_add_u32_e32 v1, v4, v1
	v_mul_hi_u32 v1, v5, v1
	v_mul_lo_u32 v3, v1, v2
	v_sub_u32_e32 v3, v5, v3
	v_add_u32_e32 v4, 1, v1
	v_cmp_ge_u32_e32 vcc, v3, v2
	s_nop 1
	v_cndmask_b32_e32 v1, v1, v4, vcc
	v_sub_u32_e32 v4, v3, v2
	v_cndmask_b32_e32 v3, v3, v4, vcc
	v_add_u32_e32 v4, 1, v1
	v_cmp_ge_u32_e32 vcc, v3, v2
	v_add_u32_e32 v3, 1, v5
	s_nop 0
	v_cndmask_b32_e32 v1, v1, v4, vcc
	v_mul_lo_u32 v4, v2, v1
	v_add_u32_e32 v2, v4, v2
	v_cmp_ne_u32_e32 vcc, v3, v2
	s_and_saveexec_b64 s[4:5], vcc
	s_xor_b64 s[4:5], exec, s[4:5]
	s_cbranch_execz .LBB0_1367
	s_waitcnt lgkmcnt(0)
	v_add_u32_e32 v1, 1, v1
	v_mul_lo_u32 v1, v1, v0
	v_mov_b32_e32 v0, 0
	s_add_u32 s34, s74, 0x1e353400
	s_addc_u32 s35, s75, 0
	global_load_dword v0, v0, s[34:35] sc1
	s_waitcnt vmcnt(0)
	v_cmp_lt_u32_e32 vcc, v0, v1
	s_and_saveexec_b64 s[8:9], vcc
	s_cbranch_execz .LBB0_1366
	s_add_u32 s14, s74, 0x1e350200
	s_addc_u32 s15, s75, 0
	s_mov_b32 s13, 1
	s_mov_b64 s[36:37], 0
	v_mov_b32_e32 v0, 0
	s_branch .LBB0_1357

.LBB0_1370:
	s_or_b64 exec, exec, s[8:9]
	v_cvt_f32_u32_e32 v3, v0
	s_waitcnt vmcnt(0)
	v_readfirstlane_b32 s4, v2
	s_add_u32 s8, s74, 0x1e353500
	s_addc_u32 s9, s75, 0
	v_rcp_iflag_f32_e32 v3, v3
	v_add_u32_e32 v1, s4, v1
	v_add_u32_e32 v4, 1, v1
	s_mov_b64 s[14:15], -1
	v_mul_f32_e32 v2, 0x4f7ffffe, v3
	v_cvt_u32_f32_e32 v2, v2
	v_sub_u32_e32 v3, 0, v0
	v_mul_lo_u32 v3, v3, v2
	v_mul_hi_u32 v3, v2, v3
	v_add_u32_e32 v2, v2, v3
	v_mul_hi_u32 v2, v1, v2
	v_mul_lo_u32 v3, v2, v0
	v_sub_u32_e32 v1, v1, v3
	v_add_u32_e32 v5, 1, v2
	v_cmp_ge_u32_e32 vcc, v1, v0
	v_sub_u32_e32 v3, v1, v0
	s_nop 0
	v_cndmask_b32_e32 v2, v2, v5, vcc
	v_cndmask_b32_e32 v1, v1, v3, vcc
	v_add_u32_e32 v3, 1, v2
	v_cmp_ge_u32_e32 vcc, v1, v0
	s_nop 1
	v_cndmask_b32_e32 v2, v2, v3, vcc
	v_mul_lo_u32 v1, v0, v2
	v_add_u32_e32 v0, v1, v0
	v_cmp_ne_u32_e32 vcc, v4, v0
	v_mov_b32_e32 v2, v0
	v_mov_b64_e32 v[0:1], s[8:9]
	s_and_saveexec_b64 s[4:5], vcc
	s_cbranch_execz .LBB0_1382
	v_mov_b32_e32 v0, 0
	global_load_dword v1, v0, s[8:9] offset:-256 sc1
	s_mov_b64 s[36:37], 0
	s_waitcnt vmcnt(0)
	v_cmp_lt_u32_e32 vcc, v1, v2
	s_and_saveexec_b64 s[34:35], vcc
	s_cbranch_execz .LBB0_1381
	s_add_u32 s14, s74, 0x1e350200
	s_addc_u32 s15, s75, 0
	s_mov_b32 s13, 1
	s_branch .LBB0_1374

.LBB0_1482:
	s_or_b64 exec, exec, s[8:9]
	v_cvt_f32_u32_e32 v4, v2
	s_waitcnt vmcnt(0)
	v_readfirstlane_b32 s6, v3
	v_sub_u32_e32 v3, 0, v2
	v_rcp_iflag_f32_e32 v4, v4
	v_add_u32_e32 v5, s6, v1
	v_mul_f32_e32 v4, 0x4f7ffffe, v4
	v_cvt_u32_f32_e32 v4, v4
	v_mul_lo_u32 v1, v3, v4
	v_mul_hi_u32 v1, v4, v1
	v_add_u32_e32 v1, v4, v1
	v_mul_hi_u32 v1, v5, v1
	v_mul_lo_u32 v3, v1, v2
	v_sub_u32_e32 v3, v5, v3
	v_add_u32_e32 v4, 1, v1
	v_cmp_ge_u32_e32 vcc, v3, v2
	s_nop 1
	v_cndmask_b32_e32 v1, v1, v4, vcc
	v_sub_u32_e32 v4, v3, v2
	v_cndmask_b32_e32 v3, v3, v4, vcc
	v_add_u32_e32 v4, 1, v1
	v_cmp_ge_u32_e32 vcc, v3, v2
	v_add_u32_e32 v3, 1, v5
	s_nop 0
	v_cndmask_b32_e32 v1, v1, v4, vcc
	v_mul_lo_u32 v4, v2, v1
	v_add_u32_e32 v2, v4, v2
	v_cmp_ne_u32_e32 vcc, v3, v2
	s_and_saveexec_b64 s[6:7], vcc
	s_xor_b64 s[6:7], exec, s[6:7]
	s_cbranch_execz .LBB0_1496
	s_waitcnt lgkmcnt(0)
	v_add_u32_e32 v1, 1, v1
	v_mul_lo_u32 v1, v1, v0
	v_mov_b32_e32 v0, 0
	s_add_u32 s16, s74, 0x1e353400
	s_addc_u32 s17, s75, 0
	global_load_dword v0, v0, s[16:17] sc1
	s_waitcnt vmcnt(0)
	v_cmp_lt_u32_e32 vcc, v0, v1
	s_and_saveexec_b64 s[8:9], vcc
	s_cbranch_execz .LBB0_1495
	s_add_u32 s14, s74, 0x1e350200
	s_addc_u32 s15, s75, 0
	s_mov_b32 s13, 1
	s_mov_b64 s[18:19], 0
	v_mov_b32_e32 v0, 0
	s_branch .LBB0_1486

.LBB0_1490:
	global_load_dword v2, v0, s[16:17] sc1
	s_add_i32 s13, s13, 1
	s_mov_b64 s[34:35], -1
	s_waitcnt vmcnt(0)
	v_cmp_ge_u32_e32 vcc, v2, v1
	s_orn2_b64 s[28:29], vcc, exec
	s_branch .LBB0_1485

.LBB0_1499:
	s_or_b64 exec, exec, s[8:9]
	v_cvt_f32_u32_e32 v3, v0
	s_waitcnt vmcnt(0)
	v_readfirstlane_b32 s6, v2
	s_add_u32 s8, s74, 0x1e353500
	s_addc_u32 s9, s75, 0
	v_rcp_iflag_f32_e32 v3, v3
	v_add_u32_e32 v1, s6, v1
	v_add_u32_e32 v4, 1, v1
	s_mov_b64 s[14:15], -1
	v_mul_f32_e32 v2, 0x4f7ffffe, v3
	v_cvt_u32_f32_e32 v2, v2
	v_sub_u32_e32 v3, 0, v0
	v_mul_lo_u32 v3, v3, v2
	v_mul_hi_u32 v3, v2, v3
	v_add_u32_e32 v2, v2, v3
	v_mul_hi_u32 v2, v1, v2
	v_mul_lo_u32 v3, v2, v0
	v_sub_u32_e32 v1, v1, v3
	v_add_u32_e32 v5, 1, v2
	v_cmp_ge_u32_e32 vcc, v1, v0
	v_sub_u32_e32 v3, v1, v0
	s_nop 0
	v_cndmask_b32_e32 v2, v2, v5, vcc
	v_cndmask_b32_e32 v1, v1, v3, vcc
	v_add_u32_e32 v3, 1, v2
	v_cmp_ge_u32_e32 vcc, v1, v0
	s_nop 1
	v_cndmask_b32_e32 v2, v2, v3, vcc
	v_mul_lo_u32 v1, v0, v2
	v_add_u32_e32 v0, v1, v0
	v_cmp_ne_u32_e32 vcc, v4, v0
	v_mov_b32_e32 v2, v0
	v_mov_b64_e32 v[0:1], s[8:9]
	s_and_saveexec_b64 s[6:7], vcc
	s_cbranch_execz .LBB0_1511
	v_mov_b32_e32 v0, 0
	global_load_dword v1, v0, s[8:9] offset:-256 sc1
	s_mov_b64 s[18:19], 0
	s_waitcnt vmcnt(0)
	v_cmp_lt_u32_e32 vcc, v1, v2
	s_and_saveexec_b64 s[16:17], vcc
	s_cbranch_execz .LBB0_1510
	s_add_u32 s14, s74, 0x1e350200
	s_addc_u32 s15, s75, 0
	s_mov_b32 s13, 1
	s_branch .LBB0_1503

.LBB0_1507:
	global_load_dword v1, v0, s[8:9] offset:-256 sc1
	s_add_i32 s13, s13, 1
	s_mov_b64 s[28:29], -1
	s_waitcnt vmcnt(0)
	v_cmp_ge_u32_e32 vcc, v1, v2
	s_orn2_b64 s[36:37], vcc, exec
	s_branch .LBB0_1502

.LBB0_1553:
	s_or_b64 exec, exec, s[6:7]
	v_cvt_f32_u32_e32 v4, v2
	s_waitcnt vmcnt(0)
	v_readfirstlane_b32 s4, v3
	v_sub_u32_e32 v3, 0, v2
	v_rcp_iflag_f32_e32 v4, v4
	v_add_u32_e32 v5, s4, v1
	v_mul_f32_e32 v4, 0x4f7ffffe, v4
	v_cvt_u32_f32_e32 v4, v4
	v_mul_lo_u32 v1, v3, v4
	v_mul_hi_u32 v1, v4, v1
	v_add_u32_e32 v1, v4, v1
	v_mul_hi_u32 v1, v5, v1
	v_mul_lo_u32 v3, v1, v2
	v_sub_u32_e32 v3, v5, v3
	v_add_u32_e32 v4, 1, v1
	v_cmp_ge_u32_e32 vcc, v3, v2
	s_nop 1
	v_cndmask_b32_e32 v1, v1, v4, vcc
	v_sub_u32_e32 v4, v3, v2
	v_cndmask_b32_e32 v3, v3, v4, vcc
	v_add_u32_e32 v4, 1, v1
	v_cmp_ge_u32_e32 vcc, v3, v2
	v_add_u32_e32 v3, 1, v5
	s_nop 0
	v_cndmask_b32_e32 v1, v1, v4, vcc
	v_mul_lo_u32 v4, v2, v1
	v_add_u32_e32 v2, v4, v2
	v_cmp_ne_u32_e32 vcc, v3, v2
	s_and_saveexec_b64 s[4:5], vcc
	s_xor_b64 s[4:5], exec, s[4:5]
	s_cbranch_execz .LBB0_1567
	s_waitcnt lgkmcnt(0)
	v_add_u32_e32 v1, 1, v1
	v_mul_lo_u32 v1, v1, v0
	v_mov_b32_e32 v0, 0
	s_add_u32 s16, s74, 0x1e353400
	s_addc_u32 s17, s75, 0
	global_load_dword v0, v0, s[16:17] sc1
	s_waitcnt vmcnt(0)
	v_cmp_lt_u32_e32 vcc, v0, v1
	s_and_saveexec_b64 s[6:7], vcc
	s_cbranch_execz .LBB0_1566
	s_add_u32 s8, s74, 0x1e350200
	s_addc_u32 s9, s75, 0
	s_mov_b32 s13, 1
	s_mov_b64 s[18:19], 0
	v_mov_b32_e32 v0, 0
	s_branch .LBB0_1557

.LBB0_1570:
	s_or_b64 exec, exec, s[6:7]
	v_cvt_f32_u32_e32 v3, v0
	s_waitcnt vmcnt(0)
	v_readfirstlane_b32 s4, v2
	s_add_u32 s6, s74, 0x1e353500
	s_addc_u32 s7, s75, 0
	v_rcp_iflag_f32_e32 v3, v3
	v_add_u32_e32 v1, s4, v1
	v_add_u32_e32 v4, 1, v1
	s_mov_b64 s[8:9], -1
	v_mul_f32_e32 v2, 0x4f7ffffe, v3
	v_cvt_u32_f32_e32 v2, v2
	v_sub_u32_e32 v3, 0, v0
	v_mul_lo_u32 v3, v3, v2
	v_mul_hi_u32 v3, v2, v3
	v_add_u32_e32 v2, v2, v3
	v_mul_hi_u32 v2, v1, v2
	v_mul_lo_u32 v3, v2, v0
	v_sub_u32_e32 v1, v1, v3
	v_add_u32_e32 v5, 1, v2
	v_cmp_ge_u32_e32 vcc, v1, v0
	v_sub_u32_e32 v3, v1, v0
	s_nop 0
	v_cndmask_b32_e32 v2, v2, v5, vcc
	v_cndmask_b32_e32 v1, v1, v3, vcc
	v_add_u32_e32 v3, 1, v2
	v_cmp_ge_u32_e32 vcc, v1, v0
	s_nop 1
	v_cndmask_b32_e32 v2, v2, v3, vcc
	v_mul_lo_u32 v1, v0, v2
	v_add_u32_e32 v0, v1, v0
	v_cmp_ne_u32_e32 vcc, v4, v0
	v_mov_b32_e32 v2, v0
	v_mov_b64_e32 v[0:1], s[6:7]
	s_and_saveexec_b64 s[4:5], vcc
	s_cbranch_execz .LBB0_1582
	v_mov_b32_e32 v0, 0
	global_load_dword v1, v0, s[6:7] offset:-256 sc1
	s_mov_b64 s[18:19], 0
	s_waitcnt vmcnt(0)
	v_cmp_lt_u32_e32 vcc, v1, v2
	s_and_saveexec_b64 s[16:17], vcc
	s_cbranch_execz .LBB0_1581
	s_add_u32 s8, s74, 0x1e350200
	s_addc_u32 s9, s75, 0
	s_mov_b32 s13, 1
	s_branch .LBB0_1574

.LBB0_1578:
	global_load_dword v1, v0, s[6:7] offset:-256 sc1
	s_add_i32 s13, s13, 1
	s_mov_b64 s[28:29], -1
	s_waitcnt vmcnt(0)
	v_cmp_ge_u32_e32 vcc, v1, v2
	s_orn2_b64 s[36:37], vcc, exec
	s_branch .LBB0_1573

.LBB0_1630:
	s_or_b64 exec, exec, s[8:9]
	v_cvt_f32_u32_e32 v4, v2
	s_waitcnt vmcnt(0)
	v_readfirstlane_b32 s4, v3
	v_sub_u32_e32 v3, 0, v2
	v_rcp_iflag_f32_e32 v4, v4
	v_add_u32_e32 v5, s4, v1
	v_mul_f32_e32 v4, 0x4f7ffffe, v4
	v_cvt_u32_f32_e32 v4, v4
	v_mul_lo_u32 v1, v3, v4
	v_mul_hi_u32 v1, v4, v1
	v_add_u32_e32 v1, v4, v1
	v_mul_hi_u32 v1, v5, v1
	v_mul_lo_u32 v3, v1, v2
	v_sub_u32_e32 v3, v5, v3
	v_add_u32_e32 v4, 1, v1
	v_cmp_ge_u32_e32 vcc, v3, v2
	s_nop 1
	v_cndmask_b32_e32 v1, v1, v4, vcc
	v_sub_u32_e32 v4, v3, v2
	v_cndmask_b32_e32 v3, v3, v4, vcc
	v_add_u32_e32 v4, 1, v1
	v_cmp_ge_u32_e32 vcc, v3, v2
	v_add_u32_e32 v3, 1, v5
	s_nop 0
	v_cndmask_b32_e32 v1, v1, v4, vcc
	v_mul_lo_u32 v4, v2, v1
	v_add_u32_e32 v2, v4, v2
	v_cmp_ne_u32_e32 vcc, v3, v2
	s_and_saveexec_b64 s[4:5], vcc
	s_xor_b64 s[4:5], exec, s[4:5]
	s_cbranch_execz .LBB0_1644
	s_waitcnt lgkmcnt(0)
	v_add_u32_e32 v1, 1, v1
	v_mul_lo_u32 v1, v1, v0
	v_mov_b32_e32 v0, 0
	s_add_u32 s16, s74, 0x1e353400
	s_addc_u32 s17, s75, 0
	global_load_dword v0, v0, s[16:17] sc1
	s_waitcnt vmcnt(0)
	v_cmp_lt_u32_e32 vcc, v0, v1
	s_and_saveexec_b64 s[8:9], vcc
	s_cbranch_execz .LBB0_1643
	s_add_u32 s14, s74, 0x1e350200
	s_addc_u32 s15, s75, 0
	s_mov_b32 s13, 1
	s_mov_b64 s[18:19], 0
	v_mov_b32_e32 v0, 0
	s_branch .LBB0_1634

.LBB0_1647:
	s_or_b64 exec, exec, s[8:9]
	v_cvt_f32_u32_e32 v3, v0
	s_waitcnt vmcnt(0)
	v_readfirstlane_b32 s4, v2
	s_add_u32 s8, s74, 0x1e353500
	s_addc_u32 s9, s75, 0
	v_rcp_iflag_f32_e32 v3, v3
	v_add_u32_e32 v1, s4, v1
	v_add_u32_e32 v4, 1, v1
	s_mov_b64 s[14:15], -1
	v_mul_f32_e32 v2, 0x4f7ffffe, v3
	v_cvt_u32_f32_e32 v2, v2
	v_sub_u32_e32 v3, 0, v0
	v_mul_lo_u32 v3, v3, v2
	v_mul_hi_u32 v3, v2, v3
	v_add_u32_e32 v2, v2, v3
	v_mul_hi_u32 v2, v1, v2
	v_mul_lo_u32 v3, v2, v0
	v_sub_u32_e32 v1, v1, v3
	v_add_u32_e32 v5, 1, v2
	v_cmp_ge_u32_e32 vcc, v1, v0
	v_sub_u32_e32 v3, v1, v0
	s_nop 0
	v_cndmask_b32_e32 v2, v2, v5, vcc
	v_cndmask_b32_e32 v1, v1, v3, vcc
	v_add_u32_e32 v3, 1, v2
	v_cmp_ge_u32_e32 vcc, v1, v0
	s_nop 1
	v_cndmask_b32_e32 v2, v2, v3, vcc
	v_mul_lo_u32 v1, v0, v2
	v_add_u32_e32 v0, v1, v0
	v_cmp_ne_u32_e32 vcc, v4, v0
	v_mov_b32_e32 v2, v0
	v_mov_b64_e32 v[0:1], s[8:9]
	s_and_saveexec_b64 s[4:5], vcc
	s_cbranch_execz .LBB0_1659
	v_mov_b32_e32 v0, 0
	global_load_dword v1, v0, s[8:9] offset:-256 sc1
	s_mov_b64 s[18:19], 0
	s_waitcnt vmcnt(0)
	v_cmp_lt_u32_e32 vcc, v1, v2
	s_and_saveexec_b64 s[16:17], vcc
	s_cbranch_execz .LBB0_1658
	s_add_u32 s14, s74, 0x1e350200
	s_addc_u32 s15, s75, 0
	s_mov_b32 s13, 1
	s_branch .LBB0_1651

.LBB0_2254:
	global_load_dword v2, v0, s[16:17] sc1
	s_add_i32 s13, s13, 1
	s_mov_b64 s[28:29], -1
	s_waitcnt vmcnt(0)
	v_cmp_ge_u32_e32 vcc, v2, v1
	s_orn2_b64 s[22:23], vcc, exec
	s_branch .LBB0_2249

.LBB0_2271:
	global_load_dword v1, v0, s[8:9] offset:-256 sc1
	s_add_i32 s13, s13, 1
	s_mov_b64 s[22:23], -1
	s_waitcnt vmcnt(0)
	v_cmp_ge_u32_e32 vcc, v1, v2
	s_orn2_b64 s[34:35], vcc, exec
	s_branch .LBB0_2266

.LBB0_2526:
	global_load_dword v2, v0, s[16:17] sc1
	s_add_i32 s13, s13, 1
	s_mov_b64 s[24:25], -1
	s_waitcnt vmcnt(0)
	v_cmp_ge_u32_e32 vcc, v2, v1
	s_orn2_b64 s[22:23], vcc, exec
	s_branch .LBB0_2521

.LBB0_2543:
	global_load_dword v1, v0, s[8:9] offset:-256 sc1
	s_add_i32 s13, s13, 1
	s_mov_b64 s[22:23], -1
	s_waitcnt vmcnt(0)
	v_cmp_ge_u32_e32 vcc, v1, v2
	s_orn2_b64 s[26:27], vcc, exec
	s_branch .LBB0_2538

.LBB0_2613:
	global_load_dword v2, v0, s[10:11] sc1
	s_add_i32 s13, s13, 1
	s_mov_b64 s[20:21], -1
	s_waitcnt vmcnt(0)
	v_cmp_ge_u32_e32 vcc, v2, v1
	s_orn2_b64 s[18:19], vcc, exec
	s_branch .LBB0_2608

.LBB0_2630:
	global_load_dword v1, v0, s[6:7] offset:-256 sc1
	s_add_i32 s13, s13, 1
	s_mov_b64 s[18:19], -1
	s_waitcnt vmcnt(0)
	v_cmp_ge_u32_e32 vcc, v1, v2
	s_orn2_b64 s[22:23], vcc, exec
	s_branch .LBB0_2625
